# v28 + NSA compressed-softmax causal mask via v_cmp(inline const, per-lane block index)+v_cndmask through rotating SGPR pairs; scan y transpose-reduce tree interleaved (1 nop instead of 7)
# speedup vs baseline: 1.0077x; 1.0027x over previous
; #define LAS __attribute__((address_space(3)))
; template <int CTRL> DI float ror_add(float x) { return x + __builtin_bit_cast(float, __builtin_amdgcn_update_dpp(0, __builtin_bit_cast(int, x), CTRL, 0xF, 0xF, true)); }
; DI void rwkv_scan2_item(KA a, LAS unsigned char* lds, const int item) {
;     ...
;             for (int t4 = 0; t4 < SC; t4 += 4) {
;                 f32x4 R4[4], W4[4], K4[4], A4[4], B4[4]; f32x2 V2[4]; float y0[4], y1[4];
; #pragma unroll
;                 for (int u = 0; u < 4; ++u) { const int o_ = (t4 + u) * 64 + 4 * kl;
;                     R4[u] = *(const LAS f32x4*)(d_ + o_); W4[u] = *(const LAS f32x4*)(d_ + SC * 64 + o_); K4[u] = *(const LAS f32x4*)(d_ + 2 * SC * 64 + o_);
;                     A4[u] = *(const LAS f32x4*)(d_ + 3 * SC * 64 + o_); B4[u] = *(const LAS f32x4*)(d_ + 4 * SC * 64 + o_); V2[u] = *(const LAS f32x2*)(d_ + 5 * SC * 64 + (t4 + u) * 32 + row0); }
; #pragma unroll
;                 for (int u = 0; u < 4; ++u) {
;                     const f32x2 a01 = {A4[u][0], A4[u][1]}, a23 = {A4[u][2], A4[u][3]}, b01 = {B4[u][0], B4[u][1]}, b23 = {B4[u][2], B4[u][3]};
;                     const f32x2 k01 = {K4[u][0], K4[u][1]}, k23 = {K4[u][2], K4[u][3]}, w01 = {W4[u][0], W4[u][1]}, w23 = {W4[u][2], W4[u][3]}, r01 = {R4[u][0], R4[u][1]}, r23 = {R4[u][2], R4[u][3]};
;                     f32x2 p0 = s00 * a01; p0 = s01 * a23 + p0; f32x2 p1 = s10 * a01; p1 = s11 * a23 + p1;
;                     float d0 = p0[0] + p0[1], d1 = p1[0] + p1[1];
;                     d0 = ror_add<0x128>(d0); d1 = ror_add<0x128>(d1); d0 = ror_add<0x124>(d0); d1 = ror_add<0x124>(d1); d0 = ror_add<0x122>(d0); d1 = ror_add<0x122>(d1); d0 = ror_add<0x121>(d0); d1 = ror_add<0x121>(d1);
;                     const float v0 = V2[u][0], v1 = V2[u][1];
;                     s00 = s00 * w01 + (k01 * v0 + b01 * d0); s01 = s01 * w23 + (k23 * v0 + b23 * d0);
;                     s10 = s10 * w01 + (k01 * v1 + b01 * d1); s11 = s11 * w23 + (k23 * v1 + b23 * d1);
;                     f32x2 q0 = s00 * r01; q0 = s01 * r23 + q0; f32x2 q1 = s10 * r01; q1 = s11 * r23 + q1;
;                     y0[u] = q0[0] + q0[1]; y1[u] = q1[0] + q1[1];
.LBB0_593:
	s_or_b64 exec, exec, s[38:39]
	s_add_i32 s29, s29, 4
	v_add_u32_e32 v36, 16, v36
	s_cmp_lt_u32 s29, 28
	s_cbranch_scc0 .LBB0_596
.LBB0_594:
	ds_read2_b64 v[84:87], v37 offset0:32 offset1:48
	ds_read_b128 v[88:91], v38 offset:512
	ds_read_b128 v[92:95], v38 offset:768
	ds_read_b128 v[96:99], v38 offset:8704
	ds_read_b128 v[100:103], v38 offset:8960
	ds_read_b128 v[104:107], v38 offset:16896
	ds_read_b128 v[108:111], v38 offset:17152
	ds_read_b128 v[112:115], v38 offset:25088
	ds_read_b128 v[116:119], v38 offset:25344
	ds_read_b128 v[120:123], v38 offset:33280
	ds_read_b128 v[124:127], v38 offset:33536
	s_waitcnt lgkmcnt(11)
	v_pk_mul_f32 v[180:181], v[22:23], v[68:69]
	v_pk_mul_f32 v[182:183], v[26:27], v[68:69]
	v_pk_fma_f32 v[180:181], v[24:25], v[70:71], v[180:181]
	v_pk_fma_f32 v[182:183], v[28:29], v[70:71], v[182:183]
	v_add_f32_e32 v210, v180, v181
	v_add_f32_e32 v212, v182, v183
	v_pk_mul_f32 v[184:185], v[60:61], v[40:41] op_sel_hi:[1,0]
	v_add_f32_dpp v210, v210, v210 row_ror:8 row_mask:0xf bank_mask:0xf bound_ctrl:1
	v_add_f32_dpp v212, v212, v212 row_ror:8 row_mask:0xf bank_mask:0xf bound_ctrl:1
	v_pk_mul_f32 v[186:187], v[62:63], v[40:41] op_sel_hi:[1,0]
	v_add_f32_dpp v210, v210, v210 row_ror:4 row_mask:0xf bank_mask:0xf bound_ctrl:1
	v_add_f32_dpp v212, v212, v212 row_ror:4 row_mask:0xf bank_mask:0xf bound_ctrl:1
	v_pk_mul_f32 v[188:189], v[60:61], v[40:41] op_sel:[0,1]
	v_add_f32_dpp v210, v210, v210 row_ror:2 row_mask:0xf bank_mask:0xf bound_ctrl:1
	v_add_f32_dpp v212, v212, v212 row_ror:2 row_mask:0xf bank_mask:0xf bound_ctrl:1
	v_pk_mul_f32 v[190:191], v[62:63], v[40:41] op_sel:[0,1]
	v_add_f32_dpp v210, v210, v210 row_ror:1 row_mask:0xf bank_mask:0xf bound_ctrl:1
	v_add_f32_dpp v212, v212, v212 row_ror:1 row_mask:0xf bank_mask:0xf bound_ctrl:1
	v_pk_fma_f32 v[184:185], v[76:77], v[210:211], v[184:185] op_sel_hi:[1,0,1]
	v_pk_fma_f32 v[186:187], v[78:79], v[210:211], v[186:187] op_sel_hi:[1,0,1]
	v_pk_fma_f32 v[188:189], v[76:77], v[212:213], v[188:189] op_sel_hi:[1,0,1]
	v_pk_fma_f32 v[190:191], v[78:79], v[212:213], v[190:191] op_sel_hi:[1,0,1]
	v_pk_fma_f32 v[22:23], v[22:23], v[52:53], v[184:185]
	v_pk_fma_f32 v[24:25], v[24:25], v[54:55], v[186:187]
	v_pk_fma_f32 v[26:27], v[26:27], v[52:53], v[188:189]
	v_pk_fma_f32 v[28:29], v[28:29], v[54:55], v[190:191]
	v_pk_mul_f32 v[206:207], v[22:23], v[44:45]
	v_pk_mul_f32 v[208:209], v[26:27], v[44:45]
	v_pk_fma_f32 v[206:207], v[24:25], v[46:47], v[206:207]
	v_pk_fma_f32 v[208:209], v[28:29], v[46:47], v[208:209]
	v_add_f32_e32 v214, v206, v207
	v_add_f32_e32 v215, v208, v209
	v_pk_mul_f32 v[180:181], v[22:23], v[72:73]
	v_pk_mul_f32 v[182:183], v[26:27], v[72:73]
	v_pk_fma_f32 v[180:181], v[24:25], v[74:75], v[180:181]
	v_pk_fma_f32 v[182:183], v[28:29], v[74:75], v[182:183]
	v_add_f32_e32 v210, v180, v181
	v_add_f32_e32 v212, v182, v183
	v_pk_mul_f32 v[184:185], v[64:65], v[42:43] op_sel_hi:[1,0]
	v_add_f32_dpp v210, v210, v210 row_ror:8 row_mask:0xf bank_mask:0xf bound_ctrl:1
	v_add_f32_dpp v212, v212, v212 row_ror:8 row_mask:0xf bank_mask:0xf bound_ctrl:1
	v_pk_mul_f32 v[186:187], v[66:67], v[42:43] op_sel_hi:[1,0]
	v_add_f32_dpp v210, v210, v210 row_ror:4 row_mask:0xf bank_mask:0xf bound_ctrl:1
	v_add_f32_dpp v212, v212, v212 row_ror:4 row_mask:0xf bank_mask:0xf bound_ctrl:1
	v_pk_mul_f32 v[188:189], v[64:65], v[42:43] op_sel:[0,1]
	v_add_f32_dpp v210, v210, v210 row_ror:2 row_mask:0xf bank_mask:0xf bound_ctrl:1
	v_add_f32_dpp v212, v212, v212 row_ror:2 row_mask:0xf bank_mask:0xf bound_ctrl:1
	v_pk_mul_f32 v[190:191], v[66:67], v[42:43] op_sel:[0,1]
	v_add_f32_dpp v210, v210, v210 row_ror:1 row_mask:0xf bank_mask:0xf bound_ctrl:1
	v_add_f32_dpp v212, v212, v212 row_ror:1 row_mask:0xf bank_mask:0xf bound_ctrl:1
	v_pk_fma_f32 v[184:185], v[80:81], v[210:211], v[184:185] op_sel_hi:[1,0,1]
	v_pk_fma_f32 v[186:187], v[82:83], v[210:211], v[186:187] op_sel_hi:[1,0,1]
	v_pk_fma_f32 v[188:189], v[80:81], v[212:213], v[188:189] op_sel_hi:[1,0,1]
	v_pk_fma_f32 v[190:191], v[82:83], v[212:213], v[190:191] op_sel_hi:[1,0,1]
	v_pk_fma_f32 v[22:23], v[22:23], v[56:57], v[184:185]
	v_pk_fma_f32 v[24:25], v[24:25], v[58:59], v[186:187]
	v_pk_fma_f32 v[26:27], v[26:27], v[56:57], v[188:189]
	v_pk_fma_f32 v[28:29], v[28:29], v[58:59], v[190:191]
	v_pk_mul_f32 v[206:207], v[22:23], v[48:49]
	v_pk_mul_f32 v[208:209], v[26:27], v[48:49]
	v_pk_fma_f32 v[206:207], v[24:25], v[50:51], v[206:207]
	v_pk_fma_f32 v[208:209], v[28:29], v[50:51], v[208:209]
	v_add_f32_e32 v216, v206, v207
	v_add_f32_e32 v217, v208, v209
	ds_read2_b64 v[40:43], v37 offset0:64 offset1:80
	ds_read_b128 v[44:47], v38 offset:1024
	ds_read_b128 v[48:51], v38 offset:1280
	ds_read_b128 v[52:55], v38 offset:9216
	ds_read_b128 v[56:59], v38 offset:9472
	ds_read_b128 v[60:63], v38 offset:17408
	ds_read_b128 v[64:67], v38 offset:17664
	ds_read_b128 v[68:71], v38 offset:25600
	ds_read_b128 v[72:75], v38 offset:25856
	ds_read_b128 v[76:79], v38 offset:33792
	ds_read_b128 v[80:83], v38 offset:34048
	s_waitcnt lgkmcnt(11)
; template <int CTRL> DI float ror_add(float x) { return x + __builtin_bit_cast(float, __builtin_amdgcn_update_dpp(0, __builtin_bit_cast(int, x), CTRL, 0xF, 0xF, true)); }
; DI void rwkv_scan2_item(KA a, LAS unsigned char* lds, const int item) {
;     ...
;                 for (int u = 0; u < 4; ++u) {
;                     const f32x2 a01 = {A4[u][0], A4[u][1]}, a23 = {A4[u][2], A4[u][3]}, b01 = {B4[u][0], B4[u][1]}, b23 = {B4[u][2], B4[u][3]};
;                     const f32x2 k01 = {K4[u][0], K4[u][1]}, k23 = {K4[u][2], K4[u][3]}, w01 = {W4[u][0], W4[u][1]}, w23 = {W4[u][2], W4[u][3]}, r01 = {R4[u][0], R4[u][1]}, r23 = {R4[u][2], R4[u][3]};
;                     f32x2 p0 = s00 * a01; p0 = s01 * a23 + p0; f32x2 p1 = s10 * a01; p1 = s11 * a23 + p1;
;                     float d0 = p0[0] + p0[1], d1 = p1[0] + p1[1];
;                     d0 = ror_add<0x128>(d0); d1 = ror_add<0x128>(d1); d0 = ror_add<0x124>(d0); d1 = ror_add<0x124>(d1); d0 = ror_add<0x122>(d0); d1 = ror_add<0x122>(d1); d0 = ror_add<0x121>(d0); d1 = ror_add<0x121>(d1);
;                     const float v0 = V2[u][0], v1 = V2[u][1];
;                     s00 = s00 * w01 + (k01 * v0 + b01 * d0); s01 = s01 * w23 + (k23 * v0 + b23 * d0);
;                     s10 = s10 * w01 + (k01 * v1 + b01 * d1); s11 = s11 * w23 + (k23 * v1 + b23 * d1);
;                     f32x2 q0 = s00 * r01; q0 = s01 * r23 + q0; f32x2 q1 = s10 * r01; q1 = s11 * r23 + q1;
;                     y0[u] = q0[0] + q0[1]; y1[u] = q1[0] + q1[1];
;                 }
;                 {
;                     const bool b3 = (kl & 8) != 0, b2 = (kl & 4) != 0, b1 = (kl & 2) != 0;
;                     float w4[4], x2[2];
; #pragma unroll
;                     for (int u = 0; u < 4; ++u) { const float keep = b3 ? y1[u] : y0[u], send = b3 ? y0[u] : y1[u]; w4[u] = keep + dppx<0x140>(send); }
; #pragma unroll
;                     for (int u = 0; u < 2; ++u) { const float keep = b2 ? w4[2 + u] : w4[u], send = b2 ? w4[u] : w4[2 + u]; x2[u] = keep + dppx<0x141>(send); }
;                     const float keep1 = b1 ? x2[1] : x2[0], send1 = b1 ? x2[0] : x2[1];
;                     float z = keep1 + dppx<0x1B>(send1);
;                     z = z + dppx<0xB1>(z);
;                     if ((kl & 1) == 0) yo[(row0 + (b3 ? 1 : 0)) * SC + t4 + (b2 ? 2 : 0) + (b1 ? 1 : 0)] = z;
	v_pk_mul_f32 v[180:181], v[22:23], v[112:113]
	v_pk_mul_f32 v[182:183], v[26:27], v[112:113]
	v_pk_fma_f32 v[180:181], v[24:25], v[114:115], v[180:181]
	v_pk_fma_f32 v[182:183], v[28:29], v[114:115], v[182:183]
	v_add_f32_e32 v210, v180, v181
	v_add_f32_e32 v212, v182, v183
	v_pk_mul_f32 v[184:185], v[104:105], v[84:85] op_sel_hi:[1,0]
	v_add_f32_dpp v210, v210, v210 row_ror:8 row_mask:0xf bank_mask:0xf bound_ctrl:1
	v_add_f32_dpp v212, v212, v212 row_ror:8 row_mask:0xf bank_mask:0xf bound_ctrl:1
	v_pk_mul_f32 v[186:187], v[106:107], v[84:85] op_sel_hi:[1,0]
	v_add_f32_dpp v210, v210, v210 row_ror:4 row_mask:0xf bank_mask:0xf bound_ctrl:1
	v_add_f32_dpp v212, v212, v212 row_ror:4 row_mask:0xf bank_mask:0xf bound_ctrl:1
	v_pk_mul_f32 v[188:189], v[104:105], v[84:85] op_sel:[0,1]
	v_add_f32_dpp v210, v210, v210 row_ror:2 row_mask:0xf bank_mask:0xf bound_ctrl:1
	v_add_f32_dpp v212, v212, v212 row_ror:2 row_mask:0xf bank_mask:0xf bound_ctrl:1
	v_pk_mul_f32 v[190:191], v[106:107], v[84:85] op_sel:[0,1]
	v_add_f32_dpp v210, v210, v210 row_ror:1 row_mask:0xf bank_mask:0xf bound_ctrl:1
	v_add_f32_dpp v212, v212, v212 row_ror:1 row_mask:0xf bank_mask:0xf bound_ctrl:1
	v_pk_fma_f32 v[184:185], v[120:121], v[210:211], v[184:185] op_sel_hi:[1,0,1]
	v_pk_fma_f32 v[186:187], v[122:123], v[210:211], v[186:187] op_sel_hi:[1,0,1]
	v_pk_fma_f32 v[188:189], v[120:121], v[212:213], v[188:189] op_sel_hi:[1,0,1]
	v_pk_fma_f32 v[190:191], v[122:123], v[212:213], v[190:191] op_sel_hi:[1,0,1]
	v_pk_fma_f32 v[22:23], v[22:23], v[96:97], v[184:185]
	v_pk_fma_f32 v[24:25], v[24:25], v[98:99], v[186:187]
	v_pk_fma_f32 v[26:27], v[26:27], v[96:97], v[188:189]
	v_pk_fma_f32 v[28:29], v[28:29], v[98:99], v[190:191]
	v_pk_mul_f32 v[206:207], v[22:23], v[88:89]
	v_pk_mul_f32 v[208:209], v[26:27], v[88:89]
	v_pk_fma_f32 v[206:207], v[24:25], v[90:91], v[206:207]
	v_pk_fma_f32 v[208:209], v[28:29], v[90:91], v[208:209]
	v_add_f32_e32 v218, v206, v207
	v_add_f32_e32 v219, v208, v209
	v_pk_mul_f32 v[180:181], v[22:23], v[116:117]
	v_pk_mul_f32 v[182:183], v[26:27], v[116:117]
	v_pk_fma_f32 v[180:181], v[24:25], v[118:119], v[180:181]
	v_pk_fma_f32 v[182:183], v[28:29], v[118:119], v[182:183]
	v_add_f32_e32 v210, v180, v181
	v_add_f32_e32 v212, v182, v183
	v_pk_mul_f32 v[184:185], v[108:109], v[86:87] op_sel_hi:[1,0]
	v_add_f32_dpp v210, v210, v210 row_ror:8 row_mask:0xf bank_mask:0xf bound_ctrl:1
	v_add_f32_dpp v212, v212, v212 row_ror:8 row_mask:0xf bank_mask:0xf bound_ctrl:1
	v_pk_mul_f32 v[186:187], v[110:111], v[86:87] op_sel_hi:[1,0]
	v_add_f32_dpp v210, v210, v210 row_ror:4 row_mask:0xf bank_mask:0xf bound_ctrl:1
	v_add_f32_dpp v212, v212, v212 row_ror:4 row_mask:0xf bank_mask:0xf bound_ctrl:1
	v_pk_mul_f32 v[188:189], v[108:109], v[86:87] op_sel:[0,1]
	v_add_f32_dpp v210, v210, v210 row_ror:2 row_mask:0xf bank_mask:0xf bound_ctrl:1
	v_add_f32_dpp v212, v212, v212 row_ror:2 row_mask:0xf bank_mask:0xf bound_ctrl:1
	v_pk_mul_f32 v[190:191], v[110:111], v[86:87] op_sel:[0,1]
	v_add_f32_dpp v210, v210, v210 row_ror:1 row_mask:0xf bank_mask:0xf bound_ctrl:1
	v_add_f32_dpp v212, v212, v212 row_ror:1 row_mask:0xf bank_mask:0xf bound_ctrl:1
	v_pk_fma_f32 v[184:185], v[124:125], v[210:211], v[184:185] op_sel_hi:[1,0,1]
	v_pk_fma_f32 v[186:187], v[126:127], v[210:211], v[186:187] op_sel_hi:[1,0,1]
	v_pk_fma_f32 v[188:189], v[124:125], v[212:213], v[188:189] op_sel_hi:[1,0,1]
	v_pk_fma_f32 v[190:191], v[126:127], v[212:213], v[190:191] op_sel_hi:[1,0,1]
	v_pk_fma_f32 v[22:23], v[22:23], v[100:101], v[184:185]
	v_pk_fma_f32 v[24:25], v[24:25], v[102:103], v[186:187]
	v_pk_fma_f32 v[26:27], v[26:27], v[100:101], v[188:189]
	v_pk_fma_f32 v[28:29], v[28:29], v[102:103], v[190:191]
	v_pk_mul_f32 v[220:221], v[22:23], v[92:93]
	v_pk_mul_f32 v[222:223], v[26:27], v[92:93]
	v_pk_fma_f32 v[220:221], v[24:25], v[94:95], v[220:221]
	v_pk_fma_f32 v[222:223], v[28:29], v[94:95], v[222:223]
	v_add_f32_e32 v220, v220, v221
	v_add_f32_e32 v221, v222, v223
	v_cndmask_b32_e64 v225, v215, v214, s[2:3]
	v_cndmask_b32_e64 v226, v214, v215, s[2:3]
	v_cndmask_b32_e64 v227, v217, v216, s[2:3]
	v_cndmask_b32_e64 v228, v216, v217, s[2:3]
	v_cndmask_b32_e64 v229, v219, v218, s[2:3]
	v_cndmask_b32_e64 v230, v218, v219, s[2:3]
	v_cndmask_b32_e64 v231, v221, v220, s[2:3]
	v_cndmask_b32_e64 v224, v220, v221, s[2:3]
	v_add_f32_dpp v214, v226, v225 row_mirror row_mask:0xf bank_mask:0xf bound_ctrl:1
	v_add_f32_dpp v216, v228, v227 row_mirror row_mask:0xf bank_mask:0xf bound_ctrl:1
	v_add_f32_dpp v218, v230, v229 row_mirror row_mask:0xf bank_mask:0xf bound_ctrl:1
	v_add_f32_dpp v220, v224, v231 row_mirror row_mask:0xf bank_mask:0xf bound_ctrl:1
	v_cndmask_b32_e64 v228, v216, v220, s[4:5]
	v_cndmask_b32_e64 v226, v214, v218, s[4:5]
	v_cndmask_b32_e64 v227, v220, v216, s[4:5]
	v_cndmask_b32_e64 v225, v218, v214, s[4:5]
	v_add_f32_dpp v216, v228, v227 row_half_mirror row_mask:0xf bank_mask:0xf bound_ctrl:1
	v_add_f32_dpp v214, v226, v225 row_half_mirror row_mask:0xf bank_mask:0xf bound_ctrl:1
	v_cndmask_b32_e64 v226, v214, v216, s[6:7]
	v_cndmask_b32_e64 v225, v216, v214, s[6:7]
	s_nop 0
	v_add_f32_dpp v214, v226, v225 quad_perm:[3,2,1,0] row_mask:0xf bank_mask:0xf bound_ctrl:1
	v_add_u32_e32 v37, 0x200, v37
	v_add_u32_e32 v38, 0x400, v38
	v_mov_b32_dpp v220, v214 quad_perm:[1,0,3,2] row_mask:0xf bank_mask:0xf bound_ctrl:1
	s_and_saveexec_b64 s[38:39], s[8:9]
	s_cbranch_execz .LBB0_593
	v_add_f32_e32 v214, v214, v220
	ds_write_b32 v36, v214
	s_branch .LBB0_593

; __device__ __forceinline__ int tid_() { int t = threadIdx.x; asm volatile("" : "+v"(t)); return t; }
; DI void nsa_item(KA a, LAS unsigned char* lds, const int it) {
;     const int tid = tid_(), lane = tid & 63, w = tid >> 6, r = lane & 31, hf = lane >> 5;
;     const int qb = 31 - (it >> 5), bg = it & 31, b = bg >> 1, g = bg & 1, hh = w >> 1, head = g * 4 + hh, tql = 32 * (w & 1) + r;
;     unsigned char* ws = a->ws; const bf16* H = (const bf16*)(ws + WS_H); bf16* act = (bf16*)(ws + WS_ACT);
;     const size_t tokrow = (size_t)b * SEQ + 64 * qb + tql;
;     LAS bf16* Kt = (LAS bf16*)(lds + NSA_KT); LAS bf16* VT = (LAS bf16*)(lds + NSA_VT); LAS float* IMP = (LAS float*)(lds + NSA_IMP); LAS float* IMPT = (LAS float*)(lds + NSA_IMPT);
;     LAS unsigned* SELM = (LAS unsigned*)(lds + NSA_SELM); LAS int* LIST = (LAS int*)(lds + NSA_LIST); LAS int* NLIST = (LAS int*)(lds + NSA_NLIST);
;     bf16x8 bq[4];
; #pragma unroll
;     for (int s = 0; s < 4; ++s) bq[s] = *(const bf16x8*)(H + tokrow * HP + C_NQ + head * 64 + 16 * s + 8 * hf);
;     const float g0 = sigmoidf_(ldbf(H + tokrow * HP + C_NG + head * 3 + 0)), g1 = sigmoidf_(ldbf(H + tokrow * HP + C_NG + head * 3 + 1)), g2 = sigmoidf_(ldbf(H + tokrow * HP + C_NG + head * 3 + 2));
;     v4u kreg; v2u vr0, vr1;
;     const int skey = tid >> 3, sch = tid & 7, sdg = tid & 15, skp = tid >> 4;
;     ...
;     NSA_LOAD(0);
;     { const bf16* kc = (const bf16*)(ws + WS_KCMP) + (size_t)bg * 128 * 64; const bf16* vc = (const bf16*)(ws + WS_VCMP) + (size_t)bg * 128 * 64;
; #pragma unroll
;       for (int i = 0; i < 2; ++i) { const int idx = tid + NTHR * i; const int c = idx >> 3, ch = idx & 7; *(LAS v4u*)(Kt + c * PA + 8 * ch) = *(const v4u*)(kc + c * 64 + 8 * ch);
;           const int dg = idx & 15, kp = idx >> 4; const v2u v0 = *(const v2u*)(vc + (2 * kp) * 64 + 4 * dg), v1 = *(const v2u*)(vc + (2 * kp + 1) * 64 + 4 * dg);
;           LAS unsigned* d0 = (LAS unsigned*)(VT + (4 * dg) * PV + vpos(2 * kp));
;           d0[0] = (v0.x & 0xffffu) | (v1.x << 16); d0[PV / 2] = (v0.x >> 16) | (v1.x & 0xffff0000u); d0[PV] = (v0.y & 0xffffu) | (v1.y << 16); d0[3 * PV / 2] = (v0.y >> 16) | (v1.y & 0xffff0000u); } }
;     ...
;         __syncthreads();
;         if (tid_() == 0) *(LAS int*)(lds + NSA_ITEM) = (int)atomicAdd(ctr, 1u);
;         __syncthreads();
;         const int it = *(LAS int*)(lds + NSA_ITEM);
;         if (it >= 1024) break;
.LBB0_607:
	s_or_b64 exec, exec, s[0:1]
	v_readlane_b32 s0, v254, 6
	s_waitcnt lgkmcnt(0)
	s_barrier
	v_mov_b32_e32 v0, s0
	ds_read_b32 v0, v0
	s_movk_i32 s0, 0x3ff
	s_waitcnt lgkmcnt(0)
	v_cmp_lt_i32_e32 vcc, s0, v0
	v_readfirstlane_b32 s2, v0
	s_mov_b64 s[0:1], -1
	s_cbranch_vccnz .LBB0_602
	s_ashr_i32 s40, s2, 5
	s_sub_i32 s3, 31, s40
	s_lshl_b32 s0, s2, 10
	v_writelane_b32 v254, s3, 47
	v_mov_b32_e32 v87, v232
	s_and_b32 s1, s2, 31
	s_and_b32 s41, s2, 1
	s_and_b32 s6, s0, 0x7800
	s_lshl_b32 s0, s3, 6
	v_readlane_b32 s2, v254, 39
	v_readlane_b32 s3, v254, 40
	v_ashrrev_i32_e32 v132, 3, v87
	v_add_u32_e32 v0, s6, v132
	s_waitcnt vmcnt(5)
	v_mov_b64_e32 v[8:9], s[2:3]
	s_movk_i32 s5, 0x1c00
	s_lshl_b32 s90, s41, 7
	v_mad_i64_i32 v[0:1], s[2:3], v0, s5, v[8:9]
	v_and_b32_e32 v133, -2, v132
	s_waitcnt vmcnt(4)
	v_lshl_add_u64 v[10:11], v[0:1], 0, s[90:91]
	v_add_u32_e32 v0, s6, v133
	v_writelane_b32 v254, s6, 48
	v_mad_i64_i32 v[0:1], s[2:3], v0, s5, v[8:9]
	s_or_b32 s90, s90, 0x1760
	s_add_i32 s4, s6, s0
	v_lshl_add_u64 v[4:5], v[0:1], 0, s[90:91]
	v_lshlrev_b32_e32 v0, 2, v87
	s_lshl_b32 s1, s1, 14
	v_readlane_b32 s2, v254, 41
	v_and_b32_e32 v136, 60, v0
	s_add_u32 s2, s2, s1
	v_readlane_b32 s3, v254, 42
	v_lshlrev_b32_e32 v0, 4, v87
	s_addc_u32 s3, s3, 0
	s_waitcnt vmcnt(3)
	v_and_b32_e32 v12, 0x70, v0
	v_mov_b32_e32 v13, v193
	s_waitcnt vmcnt(2)
	v_lshlrev_b32_e32 v14, 6, v132
	v_lshl_add_u64 v[6:7], s[2:3], 0, v[12:13]
	v_ashrrev_i32_e32 v15, 31, v14
	v_lshl_add_u64 v[0:1], v[14:15], 1, v[6:7]
	v_readlane_b32 s2, v254, 43
	v_lshlrev_b32_e32 v88, 1, v136
	v_mov_b32_e32 v89, v193
	global_load_dwordx4 v[0:3], v[0:1], off
	s_add_u32 s2, s2, s1
	v_readlane_b32 s1, v254, 46
	s_addc_u32 s3, s1, 0
	v_and_b32_e32 v18, 0xffffff80, v14
	v_or_b32_e32 v14, 64, v14
	v_lshl_add_u64 v[20:21], v[4:5], 0, v[88:89]
	s_movk_i32 s1, 0x1000
	v_lshl_add_u64 v[16:17], s[2:3], 0, v[88:89]
	v_ashrrev_i32_e32 v19, 31, v18
	v_ashrrev_i32_e32 v15, 31, v14
	v_add_co_u32_e32 v4, vcc, s1, v20
	v_lshl_add_u64 v[18:19], v[18:19], 1, v[16:17]
	v_lshl_add_u64 v[14:15], v[14:15], 1, v[16:17]
	v_addc_co_u32_e32 v5, vcc, 0, v21, vcc
	global_load_dwordx2 v[18:19], v[18:19], off
	s_nop 0
	global_load_dwordx2 v[14:15], v[14:15], off
	v_ashrrev_i32_e32 v143, 6, v87
	global_load_dwordx2 v[94:95], v[4:5], off offset:3072
	v_add_u32_e32 v4, 0x200, v87
	v_ashrrev_i32_e32 v13, 3, v4
	v_lshlrev_b32_e32 v22, 6, v13
	v_ashrrev_i32_e32 v23, 31, v22
	v_lshl_add_u64 v[4:5], v[22:23], 1, v[6:7]
	global_load_dwordx4 v[4:7], v[4:5], off
	v_and_b32_e32 v24, 0xffffff80, v22
	v_ashrrev_i32_e32 v25, 31, v24
	v_or_b32_e32 v22, 64, v22
	v_lshl_add_u64 v[24:25], v[24:25], 1, v[16:17]
	v_ashrrev_i32_e32 v23, 31, v22
	global_load_dwordx2 v[24:25], v[24:25], off
	v_lshl_add_u64 v[16:17], v[22:23], 1, v[16:17]
	global_load_dwordx2 v[16:17], v[16:17], off
	v_and_b32_e32 v89, 31, v87
	v_ashrrev_i32_e32 v146, 7, v87
	v_lshlrev_b32_e32 v22, 5, v143
	v_lshl_add_u32 v28, s41, 2, v146
	v_and_or_b32 v135, v22, 32, v89
	v_or_b32_e32 v86, s4, v135
	v_lshlrev_b32_e32 v84, 6, v28
	v_bfe_u32 v137, v87, 5, 1
	v_mad_u64_u32 v[8:9], s[2:3], v86, s5, v[8:9]
	v_ashrrev_i32_e32 v85, 31, v84
	v_lshl_add_u64 v[22:23], v[84:85], 1, v[8:9]
	v_lshlrev_b32_e32 v90, 4, v137
	v_mov_b32_e32 v91, v193
	v_lshl_add_u64 v[22:23], v[22:23], 0, v[90:91]
	s_mov_b64 s[2:3], 0x1060
	v_lshl_add_u64 v[26:27], v[22:23], 0, s[2:3]
	v_add_co_u32_e32 v22, vcc, s1, v22
	s_mov_b64 s[2:3], 0x1a60
	s_nop 0
	v_addc_co_u32_e32 v23, vcc, 0, v23, vcc
	global_load_dwordx4 v[64:67], v[26:27], off offset:32
	global_load_dwordx4 v[68:71], v[26:27], off offset:64
	global_load_dwordx4 v[72:75], v[22:23], off offset:96
	global_load_dwordx4 v[76:79], v[26:27], off offset:96
	v_lshl_add_u32 v22, v28, 1, v28
	v_ashrrev_i32_e32 v23, 31, v22
	v_lshl_add_u64 v[8:9], v[22:23], 1, v[8:9]
	v_and_b32_e32 v141, 7, v87
	v_lshl_add_u64 v[22:23], v[8:9], 0, s[2:3]
	v_add_co_u32_e32 v8, vcc, s1, v8
	v_lshlrev_b32_e32 v192, 4, v141
	s_nop 0
	v_addc_co_u32_e32 v9, vcc, 0, v9, vcc
	v_lshl_add_u64 v[10:11], v[10:11], 0, v[192:193]
	v_add_co_u32_e32 v10, vcc, s1, v10
	s_movk_i32 s4, 0x110
	s_nop 0
	v_addc_co_u32_e32 v11, vcc, 0, v11, vcc
	global_load_dword v142, v[8:9], off offset:2656
	global_load_dwordx4 v[80:83], v[10:11], off offset:1632
	global_load_dwordx2 v[96:97], v[20:21], off
	global_load_ushort v91, v[22:23], off offset:4
	v_add_u32_e32 v8, 0, v12
	v_mad_u32_u24 v9, v136, s4, 0
	v_mad_u64_u32 v[10:11], s[2:3], v132, s75, v[8:9]
	v_and_b32_e32 v140, -14, v132
	s_mov_b32 s1, 0xffff0000
	s_waitcnt vmcnt(14)
	ds_write_b128 v10, v[0:3]
	v_lshrrev_b32_e32 v0, 1, v132
	v_and_b32_e32 v138, 4, v0
	v_lshlrev_b32_e32 v0, 1, v132
	v_and_b32_e32 v139, 8, v0
	v_lshl_add_u32 v0, v140, 1, v9
	v_lshlrev_b32_e32 v1, 1, v138
	v_lshlrev_b32_e32 v2, 1, v139
	v_add3_u32 v0, v0, v1, v2
	v_add_u32_e32 v0, 0x4800, v0
	v_add_u32_e32 v112, 0, v90
	v_mad_u32_u24 v92, v89, s75, v112
	v_lshlrev_b32_e32 v93, 6, v137
	s_cmp_gt_i32 s40, 15
	s_waitcnt vmcnt(13)
	v_and_b32_e32 v1, 0xffff, v18
	v_lshrrev_b32_e32 v2, 16, v18
	s_waitcnt vmcnt(12)
	v_lshl_or_b32 v1, v14, 16, v1
	v_and_or_b32 v2, v14, s1, v2
	ds_write2_b32 v0, v1, v2 offset1:68
	v_and_b32_e32 v1, 0xffff, v19
	v_lshrrev_b32_e32 v2, 16, v19
	v_lshl_or_b32 v1, v15, 16, v1
	v_and_or_b32 v2, v15, s1, v2
	ds_write2_b32 v0, v1, v2 offset0:136 offset1:204
	v_mad_u64_u32 v[0:1], s[2:3], v13, s75, v[8:9]
	s_waitcnt vmcnt(10)
	ds_write_b128 v0, v[4:7]
	v_lshlrev_b32_e32 v0, 1, v13
	v_and_b32_e32 v0, 0xffffffe4, v0
	v_lshlrev_b32_e32 v2, 2, v13
	v_add_u32_e32 v0, v9, v0
	v_and_b32_e32 v1, 8, v13
	v_and_b32_e32 v2, 16, v2
	v_add3_u32 v0, v0, v1, v2
	s_waitcnt vmcnt(9)
	v_and_b32_e32 v1, 0xffff, v24
	v_lshrrev_b32_e32 v2, 16, v24
	s_waitcnt vmcnt(8)
	v_lshl_or_b32 v1, v16, 16, v1
	v_and_or_b32 v2, v16, s1, v2
	v_add_u32_e32 v0, 0x4800, v0
	ds_write2_b32 v0, v1, v2 offset1:68
	v_and_b32_e32 v1, 0xffff, v25
	v_lshrrev_b32_e32 v2, 16, v25
	v_lshl_or_b32 v1, v17, 16, v1
	v_and_or_b32 v2, v17, s1, v2
	ds_write2_b32 v0, v1, v2 offset0:136 offset1:204
	s_waitcnt lgkmcnt(0)
	s_barrier
; #define LAS __attribute__((address_space(3)))
; DI f32x16 mma32(bf16x8 a, bf16x8 b, f32x16 c) { return __builtin_amdgcn_mfma_f32_32x32x16_bf16(a, b, c, 0, 0, 0); }
; DI int crow(int i, int hf) { return (i & 3) + 8 * (i >> 2) + 4 * hf; }
; DI void nsa_item(KA a, LAS unsigned char* lds, const int it) {
;     ...
;         for (int k4 = 0; k4 < 4; ++k4)
; #pragma unroll
;             for (int s = 0; s < 4; ++s) { const bf16x8 af = *(const LAS bf16x8*)(Kt + (32 * k4 + r) * PA + 16 * s + 8 * hf); st[k4] = mma32(af, bq[s], st[k4]); }
;         const int tq = 64 * qb + tql; float mx = -INFINITY;
; #pragma unroll
;         for (int k4 = 0; k4 < 4; ++k4)
; #pragma unroll
;             for (int i = 0; i < 16; ++i) { const int c = 32 * k4 + crow(i, hf); const bool ok = (16 * c + 31 <= tq); st[k4][i] = ok ? st[k4][i] : -INFINITY; mx = fmaxf(mx, st[k4][i]); }
	ds_read_b128 v[170:173], v92
	ds_read_b128 v[174:177], v92 offset:32
	ds_read_b128 v[178:181], v92 offset:64
	ds_read_b128 v[182:185], v92 offset:96
	ds_read_b128 v[186:189], v92 offset:4608
	ds_read_b128 v[206:209], v92 offset:4640
	ds_read_b128 v[210:213], v92 offset:4672
	ds_read_b128 v[214:217], v92 offset:4704
	ds_read_b128 v[218:221], v92 offset:9216
	ds_read_b128 v[222:225], v92 offset:9248
	ds_read_b128 v[226:229], v92 offset:9280
	ds_read_b128 v[98:101], v92 offset:9312
	ds_read_b128 v[0:3], v92 offset:13824
	s_waitcnt vmcnt(5) lgkmcnt(12)
	v_mfma_f32_32x32x16_bf16 v[48:63], v[170:173], v[72:75], 0
	ds_read_b128 v[170:173], v92 offset:13856
	s_waitcnt lgkmcnt(12)
	v_mfma_f32_32x32x16_bf16 v[48:63], v[174:177], v[64:67], v[48:63]
	ds_read_b128 v[174:177], v92 offset:13888
	s_waitcnt lgkmcnt(12)
	v_mfma_f32_32x32x16_bf16 v[48:63], v[178:181], v[68:71], v[48:63]
	ds_read_b128 v[178:181], v92 offset:13920
	s_waitcnt vmcnt(4) lgkmcnt(12)
	v_mfma_f32_32x32x16_bf16 v[48:63], v[182:185], v[76:79], v[48:63]
	s_waitcnt lgkmcnt(11)
	v_mfma_f32_32x32x16_bf16 v[32:47], v[186:189], v[72:75], 0
	s_waitcnt lgkmcnt(10)
	v_mfma_f32_32x32x16_bf16 v[32:47], v[206:209], v[64:67], v[32:47]
	s_waitcnt lgkmcnt(9)
	v_mfma_f32_32x32x16_bf16 v[32:47], v[210:213], v[68:71], v[32:47]
	s_waitcnt lgkmcnt(8)
	v_mfma_f32_32x32x16_bf16 v[32:47], v[214:217], v[76:79], v[32:47]
	s_waitcnt lgkmcnt(7)
	v_mfma_f32_32x32x16_bf16 v[16:31], v[218:221], v[72:75], 0
	s_waitcnt lgkmcnt(6)
	v_mfma_f32_32x32x16_bf16 v[16:31], v[222:225], v[64:67], v[16:31]
	s_waitcnt lgkmcnt(5)
	v_mfma_f32_32x32x16_bf16 v[16:31], v[226:229], v[68:71], v[16:31]
	s_waitcnt lgkmcnt(4)
	v_mfma_f32_32x32x16_bf16 v[16:31], v[98:101], v[76:79], v[16:31]
	s_waitcnt lgkmcnt(3)
	v_mfma_f32_32x32x16_bf16 v[0:15], v[0:3], v[72:75], 0
	s_waitcnt lgkmcnt(2)
	v_mfma_f32_32x32x16_bf16 v[0:15], v[170:173], v[64:67], v[0:15]
	s_waitcnt lgkmcnt(1)
	v_mfma_f32_32x32x16_bf16 v[0:15], v[174:177], v[68:71], v[0:15]
	s_waitcnt lgkmcnt(0)
	v_or_b32_e32 v92, s0, v135
	s_mov_b32 s0, 0xff800000
	v_mfma_f32_32x32x16_bf16 v[0:15], v[178:181], v[76:79], v[0:15]
	v_sub_u32_e32 v243, v92, v93
	v_add_u32_e32 v243, -15, v243
	v_ashrrev_i32_e32 v243, 4, v243
	v_add_u32_e32 v242, 0xffffffc0, v243
	v_cmp_le_i32_e64 s[92:93], 1, v243
	v_cmp_le_i32_e64 s[94:95], 2, v243
	v_cmp_le_i32_e64 s[96:97], 3, v243
	v_cndmask_b32_e64 v48, v240, v48, s[92:93]
	v_cmp_le_i32_e64 s[92:93], 4, v243
	v_cndmask_b32_e64 v49, v240, v49, s[94:95]
	v_cmp_le_i32_e64 s[94:95], 9, v243
	v_max3_f32 v98, v48, s0, v49
	v_cndmask_b32_e64 v50, v240, v50, s[96:97]
	v_cmp_le_i32_e64 s[96:97], 10, v243
	v_cndmask_b32_e64 v51, v240, v51, s[92:93]
	v_cmp_le_i32_e64 s[92:93], 11, v243
	v_max3_f32 v98, v98, v50, v51
	v_cndmask_b32_e64 v52, v240, v52, s[94:95]
	v_cmp_le_i32_e64 s[94:95], 12, v243
	v_cndmask_b32_e64 v53, v240, v53, s[96:97]
	v_cmp_le_i32_e64 s[96:97], 17, v243
	v_max3_f32 v98, v98, v52, v53
	v_cndmask_b32_e64 v54, v240, v54, s[92:93]
	v_cmp_le_i32_e64 s[92:93], 18, v243
	v_cndmask_b32_e64 v55, v240, v55, s[94:95]
	v_cmp_le_i32_e64 s[94:95], 19, v243
	v_max3_f32 v98, v98, v54, v55
	v_cndmask_b32_e64 v56, v240, v56, s[96:97]
	v_cmp_le_i32_e64 s[96:97], 20, v243
	v_cndmask_b32_e64 v57, v240, v57, s[92:93]
	v_cmp_le_i32_e64 s[92:93], 25, v243
	v_max3_f32 v98, v98, v56, v57
	v_cndmask_b32_e64 v58, v240, v58, s[94:95]
	v_cmp_le_i32_e64 s[94:95], 26, v243
	v_cndmask_b32_e64 v59, v240, v59, s[96:97]
	v_cmp_le_i32_e64 s[96:97], 27, v243
	v_max3_f32 v98, v98, v58, v59
	v_cndmask_b32_e64 v60, v240, v60, s[92:93]
	v_cmp_le_i32_e64 s[92:93], 28, v243
	v_cndmask_b32_e64 v61, v240, v61, s[94:95]
	v_cmp_le_i32_e64 s[94:95], 33, v243
	v_max3_f32 v98, v98, v60, v61
	v_cndmask_b32_e64 v62, v240, v62, s[96:97]
	v_cmp_le_i32_e64 s[96:97], 34, v243
	v_cndmask_b32_e64 v63, v240, v63, s[92:93]
	v_cmp_le_i32_e64 s[92:93], 35, v243
	v_max3_f32 v98, v98, v62, v63
	v_cndmask_b32_e64 v32, v240, v32, s[94:95]
	v_cmp_le_i32_e64 s[94:95], 36, v243
	v_cndmask_b32_e64 v33, v240, v33, s[96:97]
	v_cmp_le_i32_e64 s[96:97], 41, v243
	v_max3_f32 v98, v98, v32, v33
	v_cndmask_b32_e64 v34, v240, v34, s[92:93]
	v_cmp_le_i32_e64 s[92:93], 42, v243
	v_cndmask_b32_e64 v35, v240, v35, s[94:95]
	v_cmp_le_i32_e64 s[94:95], 43, v243
	v_max3_f32 v98, v98, v34, v35
	v_cndmask_b32_e64 v36, v240, v36, s[96:97]
	v_cmp_le_i32_e64 s[96:97], 44, v243
	v_cndmask_b32_e64 v37, v240, v37, s[92:93]
	v_cmp_le_i32_e64 s[92:93], 49, v243
	v_max3_f32 v98, v98, v36, v37
	v_cndmask_b32_e64 v38, v240, v38, s[94:95]
	v_cmp_le_i32_e64 s[94:95], 50, v243
	v_cndmask_b32_e64 v39, v240, v39, s[96:97]
	v_cmp_le_i32_e64 s[96:97], 51, v243
	v_max3_f32 v98, v98, v38, v39
	v_cndmask_b32_e64 v40, v240, v40, s[92:93]
	v_cmp_le_i32_e64 s[92:93], 52, v243
	v_cndmask_b32_e64 v41, v240, v41, s[94:95]
	v_cmp_le_i32_e64 s[94:95], 57, v243
	v_max3_f32 v98, v98, v40, v41
	v_cndmask_b32_e64 v42, v240, v42, s[96:97]
	v_cmp_le_i32_e64 s[96:97], 58, v243
	v_cndmask_b32_e64 v43, v240, v43, s[92:93]
	v_cmp_le_i32_e64 s[92:93], 59, v243
	v_max3_f32 v98, v98, v42, v43
	v_cndmask_b32_e64 v44, v240, v44, s[94:95]
	v_cmp_le_i32_e64 s[94:95], 60, v243
	v_cndmask_b32_e64 v45, v240, v45, s[96:97]
	v_cmp_le_i32_e64 s[96:97], 1, v242
	v_max3_f32 v98, v98, v44, v45
	v_cndmask_b32_e64 v46, v240, v46, s[92:93]
	v_cmp_le_i32_e64 s[92:93], 2, v242
	v_cndmask_b32_e64 v47, v240, v47, s[94:95]
	v_cmp_le_i32_e64 s[94:95], 3, v242
	v_max3_f32 v98, v98, v46, v47
	v_cndmask_b32_e64 v16, v240, v16, s[96:97]
	v_cmp_le_i32_e64 s[96:97], 4, v242
	v_cndmask_b32_e64 v17, v240, v17, s[92:93]
	v_cmp_le_i32_e64 s[92:93], 9, v242
	v_max3_f32 v98, v98, v16, v17
; DI int crow(int i, int hf) { return (i & 3) + 8 * (i >> 2) + 4 * hf; }
; DI void nsa_item(KA a, LAS unsigned char* lds, const int it) {
;     ...
;         const int tq = 64 * qb + tql; float mx = -INFINITY;
; #pragma unroll
;         for (int k4 = 0; k4 < 4; ++k4)
; #pragma unroll
;             for (int i = 0; i < 16; ++i) { const int c = 32 * k4 + crow(i, hf); const bool ok = (16 * c + 31 <= tq); st[k4][i] = ok ? st[k4][i] : -INFINITY; mx = fmaxf(mx, st[k4][i]); }
;         mx = fmaxf(mx, __shfl_xor(mx, 32)); const float mref = (mx == -INFINITY) ? 0.f : mx; float ls = 0.f;
; #pragma unroll
;         for (int k4 = 0; k4 < 4; ++k4)
; #pragma unroll
;             for (int i = 0; i < 16; ++i) { const float p = __builtin_amdgcn_exp2f(st[k4][i] - mref); st[k4][i] = p; ls += p; }
;         ls += __shfl_xor(ls, 32); const float inv = ls > 0.f ? 1.f / ls : 0.f;
	v_cndmask_b32_e64 v18, v240, v18, s[94:95]
	v_cmp_le_i32_e64 s[94:95], 10, v242
	v_cndmask_b32_e64 v19, v240, v19, s[96:97]
	v_cmp_le_i32_e64 s[96:97], 11, v242
	v_max3_f32 v98, v98, v18, v19
	v_cndmask_b32_e64 v20, v240, v20, s[92:93]
	v_cmp_le_i32_e64 s[92:93], 12, v242
	v_cndmask_b32_e64 v21, v240, v21, s[94:95]
	v_cmp_le_i32_e64 s[94:95], 17, v242
	v_max3_f32 v98, v98, v20, v21
	v_cndmask_b32_e64 v22, v240, v22, s[96:97]
	v_cmp_le_i32_e64 s[96:97], 18, v242
	v_cndmask_b32_e64 v23, v240, v23, s[92:93]
	v_cmp_le_i32_e64 s[92:93], 19, v242
	v_max3_f32 v98, v98, v22, v23
	v_cndmask_b32_e64 v24, v240, v24, s[94:95]
	v_cmp_le_i32_e64 s[94:95], 20, v242
	v_cndmask_b32_e64 v25, v240, v25, s[96:97]
	v_cmp_le_i32_e64 s[96:97], 25, v242
	v_max3_f32 v98, v98, v24, v25
	v_cndmask_b32_e64 v26, v240, v26, s[92:93]
	v_cmp_le_i32_e64 s[92:93], 26, v242
	v_cndmask_b32_e64 v27, v240, v27, s[94:95]
	v_cmp_le_i32_e64 s[94:95], 27, v242
	v_max3_f32 v98, v98, v26, v27
	v_cndmask_b32_e64 v28, v240, v28, s[96:97]
	v_cmp_le_i32_e64 s[96:97], 28, v242
	v_cndmask_b32_e64 v29, v240, v29, s[92:93]
	v_cmp_le_i32_e64 s[92:93], 33, v242
	v_max3_f32 v98, v98, v28, v29
	v_cndmask_b32_e64 v30, v240, v30, s[94:95]
	v_cmp_le_i32_e64 s[94:95], 34, v242
	v_cndmask_b32_e64 v31, v240, v31, s[96:97]
	v_cmp_le_i32_e64 s[96:97], 35, v242
	v_max3_f32 v98, v98, v30, v31
	v_cndmask_b32_e64 v113, v240, v0, s[92:93]
	v_cmp_le_i32_e64 s[92:93], 36, v242
	v_cndmask_b32_e64 v116, v240, v1, s[94:95]
	v_cmp_le_i32_e64 s[94:95], 41, v242
	v_max3_f32 v0, v98, v113, v116
	v_cndmask_b32_e64 v117, v240, v2, s[96:97]
	v_cmp_le_i32_e64 s[96:97], 42, v242
	v_and_b32_e32 v2, 64, v238
	v_cndmask_b32_e64 v130, v240, v3, s[92:93]
	v_cmp_le_i32_e64 s[92:93], 43, v242
	v_max3_f32 v0, v0, v117, v130
	v_cndmask_b32_e64 v131, v240, v4, s[94:95]
	v_cmp_le_i32_e64 s[94:95], 44, v242
	v_add_u32_e32 v144, 64, v2
	v_cndmask_b32_e64 v145, v240, v5, s[96:97]
	v_cmp_le_i32_e64 s[96:97], 49, v242
	v_max3_f32 v0, v0, v131, v145
	v_cndmask_b32_e64 v147, v240, v6, s[92:93]
	v_cmp_le_i32_e64 s[92:93], 50, v242
	v_cndmask_b32_e64 v148, v240, v7, s[94:95]
	v_cmp_le_i32_e64 s[94:95], 51, v242
	v_max3_f32 v0, v0, v147, v148
	v_cndmask_b32_e64 v149, v240, v8, s[96:97]
	v_cmp_le_i32_e64 s[96:97], 52, v242
	v_cndmask_b32_e64 v150, v240, v9, s[92:93]
	v_cmp_le_i32_e64 s[92:93], 57, v242
	v_max3_f32 v0, v0, v149, v150
	v_cndmask_b32_e64 v10, v240, v10, s[94:95]
	v_cmp_le_i32_e64 s[94:95], 58, v242
	v_cndmask_b32_e64 v11, v240, v11, s[96:97]
	v_cmp_le_i32_e64 s[96:97], 59, v242
	v_max3_f32 v0, v0, v10, v11
	v_cndmask_b32_e64 v12, v240, v12, s[92:93]
	v_cmp_le_i32_e64 s[92:93], 60, v242
	v_cndmask_b32_e64 v13, v240, v13, s[94:95]
	v_max3_f32 v0, v0, v12, v13
	v_cndmask_b32_e64 v14, v240, v14, s[96:97]
	v_xor_b32_e32 v1, 32, v238
	v_cndmask_b32_e64 v15, v240, v15, s[92:93]
	v_cmp_lt_i32_e32 vcc, v1, v144
	v_max3_f32 v0, v0, v14, v15
	s_nop 0
	v_cndmask_b32_e32 v1, v238, v1, vcc
	v_lshlrev_b32_e32 v134, 2, v1
	v_mov_b32_e32 v1, v0
	s_waitcnt lgkmcnt(0)
	s_nop 1
	v_permlane32_swap_b32_e32 v1, v0
	v_max_f32_e32 v0, v0, v1
	v_cmp_neq_f32_e32 vcc, s0, v0
	s_nop 1
	v_cndmask_b32_e32 v151, 0, v0, vcc
	v_sub_f32_e32 v0, v48, v151
	v_exp_f32_e32 v0, v0
	v_sub_f32_e32 v1, v49, v151
	v_exp_f32_e32 v1, v1
	v_sub_f32_e32 v2, v50, v151
	v_exp_f32_e32 v2, v2
	v_sub_f32_e32 v3, v51, v151
	v_exp_f32_e32 v3, v3
	v_add_f32_e32 v4, 0, v0
	v_add_f32_e32 v4, v1, v4
	v_add_f32_e32 v4, v2, v4
	v_add_f32_e32 v8, v3, v4
	v_sub_f32_e32 v4, v52, v151
	v_exp_f32_e32 v4, v4
	v_sub_f32_e32 v5, v53, v151
	v_exp_f32_e32 v5, v5
	v_sub_f32_e32 v6, v54, v151
	v_exp_f32_e32 v6, v6
	v_sub_f32_e32 v7, v55, v151
	v_exp_f32_e32 v7, v7
	v_sub_f32_e32 v9, v56, v151
	v_add_f32_e32 v8, v4, v8
	v_exp_f32_e32 v126, v9
	v_sub_f32_e32 v9, v57, v151
	v_add_f32_e32 v8, v5, v8
	v_exp_f32_e32 v127, v9
	v_sub_f32_e32 v9, v58, v151
	v_add_f32_e32 v8, v6, v8
	v_exp_f32_e32 v98, v9
	v_sub_f32_e32 v9, v59, v151
	v_add_f32_e32 v8, v7, v8
	v_exp_f32_e32 v99, v9
	v_add_f32_e32 v8, v126, v8
	v_add_f32_e32 v8, v127, v8
	v_add_f32_e32 v8, v98, v8
	v_add_f32_e32 v48, v99, v8
	v_sub_f32_e32 v8, v60, v151
	v_exp_f32_e32 v122, v8
	v_sub_f32_e32 v8, v61, v151
	v_exp_f32_e32 v123, v8
	v_sub_f32_e32 v8, v62, v151
	v_exp_f32_e32 v8, v8
	v_sub_f32_e32 v9, v63, v151
	v_exp_f32_e32 v9, v9
	v_sub_f32_e32 v32, v32, v151
	v_add_f32_e32 v48, v122, v48
	v_exp_f32_e32 v106, v32
	v_sub_f32_e32 v32, v33, v151
	v_add_f32_e32 v48, v123, v48
	v_exp_f32_e32 v107, v32
	v_sub_f32_e32 v32, v34, v151
	v_add_f32_e32 v48, v8, v48
	v_exp_f32_e32 v114, v32
	v_sub_f32_e32 v32, v35, v151
	v_add_f32_e32 v48, v9, v48
	v_exp_f32_e32 v115, v32
	v_sub_f32_e32 v33, v36, v151
	v_add_f32_e32 v32, v106, v48
	v_exp_f32_e32 v120, v33
	v_sub_f32_e32 v33, v37, v151
	v_add_f32_e32 v32, v107, v32
	v_exp_f32_e32 v121, v33
	v_sub_f32_e32 v33, v38, v151
	v_add_f32_e32 v32, v114, v32
	v_exp_f32_e32 v128, v33
	v_sub_f32_e32 v33, v39, v151
	v_add_f32_e32 v32, v115, v32
	v_exp_f32_e32 v129, v33
	v_sub_f32_e32 v33, v40, v151
	v_add_f32_e32 v32, v120, v32
	v_exp_f32_e32 v104, v33
	v_sub_f32_e32 v33, v41, v151
	v_add_f32_e32 v32, v121, v32
	v_exp_f32_e32 v105, v33
	v_sub_f32_e32 v33, v42, v151
	v_add_f32_e32 v32, v128, v32
	v_exp_f32_e32 v110, v33
	v_sub_f32_e32 v33, v43, v151
	v_add_f32_e32 v32, v129, v32
	v_exp_f32_e32 v111, v33
	v_sub_f32_e32 v33, v44, v151
	v_add_f32_e32 v32, v104, v32
	v_exp_f32_e32 v118, v33
	v_sub_f32_e32 v33, v45, v151
	v_add_f32_e32 v32, v105, v32
	v_exp_f32_e32 v119, v33
	v_sub_f32_e32 v33, v46, v151
	v_add_f32_e32 v32, v110, v32
	v_exp_f32_e32 v124, v33
	v_sub_f32_e32 v33, v47, v151
	v_add_f32_e32 v32, v111, v32
; DI f32x16 mma32(bf16x8 a, bf16x8 b, f32x16 c) { return __builtin_amdgcn_mfma_f32_32x32x16_bf16(a, b, c, 0, 0, 0); }
; DI bf16x8 packp(const f32x16& x, const int h8) { v4u p; p.x = pk2(x[h8 + 0], x[h8 + 1]); p.y = pk2(x[h8 + 2], x[h8 + 3]); p.z = pk2(x[h8 + 4], x[h8 + 5]); p.w = pk2(x[h8 + 6], x[h8 + 7]); return __builtin_bit_cast(bf16x8, p); }
; DI void nsa_item(KA a, LAS unsigned char* lds, const int it) {
;     ...
;         for (int k4 = 0; k4 < 4; ++k4)
; #pragma unroll
;             for (int i = 0; i < 16; ++i) { const float p = __builtin_amdgcn_exp2f(st[k4][i] - mref); st[k4][i] = p; ls += p; }
;         ls += __shfl_xor(ls, 32); const float inv = ls > 0.f ? 1.f / ls : 0.f;
; #pragma unroll
;         for (int k4 = 0; k4 < 4; ++k4) st[k4] = st[k4] * inv;
;         f32x16 ot[2] = {ZERO16, ZERO16};
; #pragma unroll
;         for (int sp = 0; sp < 8; ++sp) { const bf16x8 pf = packp(st[sp >> 1], 8 * (sp & 1));
; #pragma unroll
;             for (int dh = 0; dh < 2; ++dh) ot[dh] = mma32(vfrag(VT, 32 * dh + r, sp, hf), pf, ot[dh]); }
	v_exp_f32_e32 v125, v33
	v_sub_f32_e32 v16, v16, v151
	v_add_f32_e32 v32, v118, v32
	v_exp_f32_e32 v52, v16
	v_sub_f32_e32 v16, v17, v151
	v_add_f32_e32 v32, v119, v32
	v_exp_f32_e32 v53, v16
	v_sub_f32_e32 v16, v18, v151
	v_add_f32_e32 v32, v124, v32
	v_exp_f32_e32 v60, v16
	v_sub_f32_e32 v16, v19, v151
	v_add_f32_e32 v32, v125, v32
	v_exp_f32_e32 v61, v16
	v_sub_f32_e32 v17, v20, v151
	v_add_f32_e32 v16, v52, v32
	v_exp_f32_e32 v100, v17
	v_sub_f32_e32 v17, v21, v151
	v_add_f32_e32 v16, v53, v16
	v_exp_f32_e32 v101, v17
	v_sub_f32_e32 v17, v22, v151
	v_add_f32_e32 v16, v60, v16
	v_exp_f32_e32 v108, v17
	v_sub_f32_e32 v17, v23, v151
	v_add_f32_e32 v16, v61, v16
	v_exp_f32_e32 v109, v17
	v_sub_f32_e32 v17, v24, v151
	v_add_f32_e32 v16, v100, v16
	v_exp_f32_e32 v48, v17
	v_sub_f32_e32 v17, v25, v151
	v_add_f32_e32 v16, v101, v16
	v_exp_f32_e32 v49, v17
	v_sub_f32_e32 v17, v26, v151
	v_add_f32_e32 v16, v108, v16
	v_exp_f32_e32 v56, v17
	v_sub_f32_e32 v17, v27, v151
	v_add_f32_e32 v16, v109, v16
	v_exp_f32_e32 v57, v17
	v_sub_f32_e32 v17, v28, v151
	v_add_f32_e32 v16, v48, v16
	v_exp_f32_e32 v92, v17
	v_sub_f32_e32 v17, v29, v151
	v_add_f32_e32 v16, v49, v16
	v_exp_f32_e32 v93, v17
	v_sub_f32_e32 v17, v30, v151
	v_add_f32_e32 v16, v56, v16
	v_exp_f32_e32 v102, v17
	v_sub_f32_e32 v17, v31, v151
	v_add_f32_e32 v16, v57, v16
	v_exp_f32_e32 v103, v17
	v_sub_f32_e32 v17, v113, v151
	v_add_f32_e32 v16, v92, v16
	v_exp_f32_e32 v34, v17
	v_sub_f32_e32 v17, v116, v151
	v_add_f32_e32 v16, v93, v16
	v_exp_f32_e32 v35, v17
	v_sub_f32_e32 v17, v117, v151
	v_add_f32_e32 v16, v102, v16
	v_exp_f32_e32 v38, v17
	v_sub_f32_e32 v17, v130, v151
	v_add_f32_e32 v16, v103, v16
	v_exp_f32_e32 v39, v17
	v_sub_f32_e32 v17, v131, v151
	v_add_f32_e32 v16, v34, v16
	v_exp_f32_e32 v42, v17
	v_sub_f32_e32 v17, v145, v151
	v_add_f32_e32 v16, v35, v16
	v_exp_f32_e32 v43, v17
	v_sub_f32_e32 v17, v147, v151
	v_add_f32_e32 v16, v38, v16
	v_exp_f32_e32 v54, v17
	v_sub_f32_e32 v17, v148, v151
	v_add_f32_e32 v16, v39, v16
	v_exp_f32_e32 v55, v17
	v_sub_f32_e32 v17, v149, v151
	v_add_f32_e32 v16, v42, v16
	v_exp_f32_e32 v32, v17
	v_sub_f32_e32 v17, v150, v151
	v_add_f32_e32 v16, v43, v16
	v_exp_f32_e32 v33, v17
	v_sub_f32_e32 v10, v10, v151
	v_add_f32_e32 v16, v54, v16
	v_exp_f32_e32 v36, v10
	v_sub_f32_e32 v10, v11, v151
	v_add_f32_e32 v16, v55, v16
	v_exp_f32_e32 v37, v10
	v_sub_f32_e32 v11, v12, v151
	v_add_f32_e32 v10, v32, v16
	v_exp_f32_e32 v40, v11
	v_sub_f32_e32 v11, v13, v151
	v_add_f32_e32 v10, v33, v10
	v_exp_f32_e32 v41, v11
	v_sub_f32_e32 v11, v14, v151
	v_add_f32_e32 v10, v36, v10
	v_exp_f32_e32 v44, v11
	v_sub_f32_e32 v11, v15, v151
	v_add_f32_e32 v10, v37, v10
	v_exp_f32_e32 v45, v11
	v_add_f32_e32 v10, v40, v10
	v_add_f32_e32 v10, v41, v10
	v_add_f32_e32 v10, v44, v10
	v_add_f32_e32 v10, v45, v10
	v_mov_b32_e32 v11, v10
	v_mad_u32_u24 v59, v89, s4, v112
	s_waitcnt lgkmcnt(0)
	s_nop 1
	v_permlane32_swap_b32_e32 v11, v10
	v_add_f32_e32 v10, v10, v11
	v_div_scale_f32 v11, s[0:1], v10, v10, 1.0
	v_rcp_f32_e32 v12, v11
	s_mov_b64 s[0:1], -1
	v_fma_f32 v13, -v11, v12, 1.0
	v_fmac_f32_e32 v12, v13, v12
	v_div_scale_f32 v13, vcc, 1.0, v10, 1.0
	v_mul_f32_e32 v14, v13, v12
	v_fma_f32 v15, -v11, v14, v13
	v_fmac_f32_e32 v14, v15, v12
	v_fma_f32 v11, -v11, v14, v13
	v_div_fmas_f32 v11, v11, v12, v14
	v_div_fixup_f32 v11, v11, v10, 1.0
	v_cmp_lt_f32_e32 vcc, 0, v10
	s_nop 1
	v_cndmask_b32_e32 v58, 0, v11, vcc
	ds_read_b128 v[10:13], v59 offset:18432
	v_pk_mul_f32 v[46:47], v[6:7], v[58:59] op_sel_hi:[1,0]
	v_pk_mul_f32 v[112:113], v[4:5], v[58:59] op_sel_hi:[1,0]
	v_pk_mul_f32 v[50:51], v[2:3], v[58:59] op_sel_hi:[1,0]
	v_pk_mul_f32 v[116:117], v[0:1], v[58:59] op_sel_hi:[1,0]
	v_cvt_pk_bf16_f32 v1, v50, v51
	v_cvt_pk_bf16_f32 v0, v116, v117
	v_cvt_pk_bf16_f32 v2, v112, v113
	v_cvt_pk_bf16_f32 v3, v46, v47
	ds_read_b128 v[4:7], v59 offset:27136
	ds_read_b128 v[148:151], v59 offset:18464
	s_waitcnt lgkmcnt(2)
	v_mfma_f32_32x32x16_bf16 v[16:31], v[10:13], v[0:3], 0
	v_mul_f32_e64 v62, v8, v58
	v_mul_f32_e64 v63, v9, v58
	v_mul_f32_e64 v122, v122, v58
	v_mul_f32_e64 v123, v123, v58
	v_mul_f32_e64 v98, v98, v58
	v_mul_f32_e64 v99, v99, v58
	v_pk_mul_f32 v[126:127], v[126:127], v[58:59] op_sel_hi:[1,0]
	v_cvt_pk_bf16_f32 v153, v98, v99
	v_cvt_pk_bf16_f32 v152, v126, v127
	v_cvt_pk_bf16_f32 v154, v122, v123
	v_cvt_pk_bf16_f32 v155, v62, v63
	s_waitcnt lgkmcnt(1)
; DI f32x16 mma32(bf16x8 a, bf16x8 b, f32x16 c) { return __builtin_amdgcn_mfma_f32_32x32x16_bf16(a, b, c, 0, 0, 0); }
; DI bf16x8 packp(const f32x16& x, const int h8) { v4u p; p.x = pk2(x[h8 + 0], x[h8 + 1]); p.y = pk2(x[h8 + 2], x[h8 + 3]); p.z = pk2(x[h8 + 4], x[h8 + 5]); p.w = pk2(x[h8 + 6], x[h8 + 7]); return __builtin_bit_cast(bf16x8, p); }
; DI void nsa_item(KA a, LAS unsigned char* lds, const int it) {
;     ...
;         for (int k4 = 0; k4 < 4; ++k4) st[k4] = st[k4] * inv;
;         f32x16 ot[2] = {ZERO16, ZERO16};
; #pragma unroll
;         for (int sp = 0; sp < 8; ++sp) { const bf16x8 pf = packp(st[sp >> 1], 8 * (sp & 1));
; #pragma unroll
;             for (int dh = 0; dh < 2; ++dh) ot[dh] = mma32(vfrag(VT, 32 * dh + r, sp, hf), pf, ot[dh]); }
;         of[0] = ot[0] * g0; of[1] = ot[1] * g0;
;         if (qb >= 16) {
	v_mfma_f32_32x32x16_bf16 v[0:15], v[4:7], v[0:3], 0
	ds_read_b128 v[156:159], v59 offset:18496
	v_mul_f32_e64 v128, v128, v58
	v_mul_f32_e64 v129, v129, v58
	v_mul_f32_e64 v120, v120, v58
	v_mul_f32_e64 v121, v121, v58
	v_pk_mul_f32 v[114:115], v[114:115], v[58:59] op_sel_hi:[1,0]
	v_pk_mul_f32 v[130:131], v[106:107], v[58:59] op_sel_hi:[1,0]
	v_pk_mul_f32 v[106:107], v[124:125], v[58:59] op_sel_hi:[1,0]
	v_pk_mul_f32 v[118:119], v[118:119], v[58:59] op_sel_hi:[1,0]
	s_waitcnt lgkmcnt(1)
	v_mfma_f32_32x32x16_bf16 v[16:31], v[148:151], v[152:155], v[16:31]
	ds_read_b128 v[148:151], v59 offset:27168
	v_mul_f32_e64 v110, v110, v58
	v_mul_f32_e64 v111, v111, v58
	v_mul_f32_e64 v104, v104, v58
	v_mul_f32_e64 v105, v105, v58
	v_pk_mul_f32 v[108:109], v[108:109], v[58:59] op_sel_hi:[1,0]
	v_pk_mul_f32 v[100:101], v[100:101], v[58:59] op_sel_hi:[1,0]
	v_pk_mul_f32 v[60:61], v[60:61], v[58:59] op_sel_hi:[1,0]
	v_pk_mul_f32 v[124:125], v[52:53], v[58:59] op_sel_hi:[1,0]
	s_waitcnt lgkmcnt(0)
	v_mfma_f32_32x32x16_bf16 v[0:15], v[148:151], v[152:155], v[0:15]
	v_cvt_pk_bf16_f32 v148, v130, v131
	v_cvt_pk_bf16_f32 v149, v114, v115
	v_cvt_pk_bf16_f32 v150, v120, v121
	v_cvt_pk_bf16_f32 v151, v128, v129
	v_mul_f32_e64 v52, v102, v58
	v_mul_f32_e64 v53, v103, v58
	v_pk_mul_f32 v[102:103], v[92:93], v[58:59] op_sel_hi:[1,0]
	v_pk_mul_f32 v[56:57], v[56:57], v[58:59] op_sel_hi:[1,0]
	v_mfma_f32_32x32x16_bf16 v[16:31], v[156:159], v[148:151], v[16:31]
	ds_read_b128 v[152:155], v59 offset:27200
	ds_read_b128 v[156:159], v59 offset:18528
	v_mul_f32_e64 v48, v48, v58
	v_mul_f32_e64 v49, v49, v58
	v_mul_f32_e64 v54, v54, v58
	v_mul_f32_e64 v55, v55, v58
	v_pk_mul_f32 v[42:43], v[42:43], v[58:59] op_sel_hi:[1,0]
	v_pk_mul_f32 v[38:39], v[38:39], v[58:59] op_sel_hi:[1,0]
	v_pk_mul_f32 v[34:35], v[34:35], v[58:59] op_sel_hi:[1,0]
	v_pk_mul_f32 v[44:45], v[44:45], v[58:59] op_sel_hi:[1,0]
	s_waitcnt lgkmcnt(1)
	v_mfma_f32_32x32x16_bf16 v[0:15], v[152:155], v[148:151], v[0:15]
	ds_read_b128 v[152:155], v59 offset:27232
	v_cvt_pk_bf16_f32 v148, v104, v105
	v_cvt_pk_bf16_f32 v149, v110, v111
	v_cvt_pk_bf16_f32 v150, v118, v119
	v_cvt_pk_bf16_f32 v151, v106, v107
	v_pk_mul_f32 v[40:41], v[40:41], v[58:59] op_sel_hi:[1,0]
	v_pk_mul_f32 v[36:37], v[36:37], v[58:59] op_sel_hi:[1,0]
	s_waitcnt lgkmcnt(1)
	v_mfma_f32_32x32x16_bf16 v[16:31], v[156:159], v[148:151], v[16:31]
	ds_read_b128 v[156:159], v59 offset:18560
	v_mul_f32_e64 v32, v32, v58
	v_mul_f32_e64 v33, v33, v58
	v_lshlrev_b32_e32 v58, 2, v141
	s_waitcnt lgkmcnt(1)
	v_mfma_f32_32x32x16_bf16 v[0:15], v[152:155], v[148:151], v[0:15]
	v_cvt_pk_bf16_f32 v148, v124, v125
	v_cvt_pk_bf16_f32 v149, v60, v61
	v_cvt_pk_bf16_f32 v150, v100, v101
	v_cvt_pk_bf16_f32 v151, v108, v109
	s_waitcnt lgkmcnt(0)
	s_nop 0
	v_mfma_f32_32x32x16_bf16 v[16:31], v[156:159], v[148:151], v[16:31]
	ds_read_b128 v[152:155], v59 offset:27264
	ds_read_b128 v[156:159], v59 offset:18592
	s_waitcnt lgkmcnt(1)
	v_mfma_f32_32x32x16_bf16 v[0:15], v[152:155], v[148:151], v[0:15]
	ds_read_b128 v[152:155], v59 offset:27296
	v_cvt_pk_bf16_f32 v148, v48, v49
	v_cvt_pk_bf16_f32 v149, v56, v57
	v_cvt_pk_bf16_f32 v150, v102, v103
	v_cvt_pk_bf16_f32 v151, v52, v53
	s_waitcnt lgkmcnt(1)
	s_nop 0
	v_mfma_f32_32x32x16_bf16 v[16:31], v[156:159], v[148:151], v[16:31]
	ds_read_b128 v[156:159], v59 offset:18624
	s_waitcnt lgkmcnt(1)
	v_mfma_f32_32x32x16_bf16 v[0:15], v[152:155], v[148:151], v[0:15]
	v_cvt_pk_bf16_f32 v148, v34, v35
	v_cvt_pk_bf16_f32 v149, v38, v39
	v_cvt_pk_bf16_f32 v150, v42, v43
	v_cvt_pk_bf16_f32 v151, v54, v55
	s_waitcnt lgkmcnt(0)
	s_nop 0
	v_mfma_f32_32x32x16_bf16 v[16:31], v[156:159], v[148:151], v[16:31]
	ds_read_b128 v[152:155], v59 offset:27328
	ds_read_b128 v[156:159], v59 offset:18656
	s_waitcnt lgkmcnt(1)
	v_mfma_f32_32x32x16_bf16 v[0:15], v[152:155], v[148:151], v[0:15]
	ds_read_b128 v[152:155], v59 offset:27360
	v_cvt_pk_bf16_f32 v148, v32, v33
	v_cvt_pk_bf16_f32 v149, v36, v37
	v_cvt_pk_bf16_f32 v150, v40, v41
	v_cvt_pk_bf16_f32 v151, v44, v45
	s_waitcnt lgkmcnt(1)
	s_nop 0
	v_mfma_f32_32x32x16_bf16 v[16:31], v[156:159], v[148:151], v[16:31]
	s_waitcnt lgkmcnt(0)
	v_mfma_f32_32x32x16_bf16 v[0:15], v[152:155], v[148:151], v[0:15]
	s_cbranch_scc0 .LBB0_610
	v_lshlrev_b32_e32 v145, 2, v141
	s_mov_b64 s[0:1], 0
